# attention phase entry: the wait for the lambda input loads is moved down to their first use (56 independent set-up instructions later)
# baseline (speedup 1.0000x reference)
; #define LAS __attribute__((address_space(3)))
; template <int DV, int NMAP>
; __device__ __forceinline__ void attn_unit(LAS unsigned char* lds, const bf16_t* U, bf16_t* MIX, const float* logf, int b, int h, int qb, float lam, float slope2, const float* gn, float outscale, const int tid) {
;     ...
;             float incl = 0.f, wsum = 0.f;
; #pragma unroll
;             for (int j4 = 0; j4 < 16; ++j4) { const f32x4 t = *(const LAS f32x4*)(tots + wid * 64 + 4 * j4);
; #pragma unroll
;                 for (int i = 0; i < 4; ++i) { wsum += t[i]; incl += (4 * j4 + i <= lane) ? t[i] : 0.f; } }
; __device__ __forceinline__ void attn_phase(const Args& a, int l, LAS unsigned char* lds, const int tid, const int rep) {
;     const int lane = tid & 63;
;     unsigned char* ws = a.ws;
;     const bf16_t* U = (const bf16_t*)(ws + WS_U); bf16_t* MIX = (bf16_t*)(ws + WS_MIX); const float* logf = (const float*)(ws + WS_LOGF);
;     unsigned* ctr = (unsigned*)(ws + WS_CTR) + l + 2 * rep;
;     int lop = l; asm volatile("" : "+s"(lop));
;     const float lam_init = 0.8f - 0.6f * expf(-0.3f * (float)lop);
;     float lam;
;     {
;         const float* lv = a.in[10] + l * 256;
;         const float sa = wave_sum(lv[lane] * lv[64 + lane]), sb = wave_sum(lv[128 + lane] * lv[192 + lane]);
;         lam = expf(sa) - expf(sb) + lam_init;
;     }
;     const float* gn = a.in[11] + l * 128;
.LBB0_172:
	s_and_b64 vcc, exec, s[0:1]
	s_cbranch_vccz .LBB0_234
	s_cmp_gt_i32 s5, 0
	s_mov_b64 s[0:1], -1
	s_cbranch_scc0 .LBB0_236
	v_and_b32_e32 v123, 63, v188
	v_readlane_b32 s2, v252, 18
	v_readlane_b32 s0, v252, 29
	v_lshlrev_b32_e32 v0, 2, v123
	v_readlane_b32 s3, v252, 19
	s_nop 4
	global_load_dword v4, v0, s[2:3]
	global_load_dword v5, v0, s[2:3] offset:256
	global_load_dword v6, v0, s[2:3] offset:512
	global_load_dword v7, v0, s[2:3] offset:768
	v_readlane_b32 s1, v252, 30
	v_cmp_gt_u32_e64 s[6:7], 7, v123
	v_readlane_b32 s1, v253, 33
	s_lshl_b32 s20, s1, 1
	v_writelane_b32 v253, s6, 36
	s_lshl_b64 s[2:3], s[20:21], 2
	v_readlane_b32 s1, v252, 8
	v_writelane_b32 v253, s7, 37
	v_cmp_gt_u32_e64 s[6:7], 8, v123
	s_add_u32 s52, s1, s2
	s_mov_b32 s1, 0xc2ce8ed0
	v_writelane_b32 v253, s6, 38
	v_add_u32_e32 v131, 0, v0
	v_mov_b32_e32 v0, 0x3f4ccccd
	v_writelane_b32 v253, s7, 39
	v_cmp_gt_u32_e64 s[6:7], 9, v123
	v_bfe_u32 v2, v188, 5, 1
	v_lshlrev_b32_e32 v130, 2, v2
	v_writelane_b32 v253, s6, 40
	v_lshlrev_b32_e32 v8, 3, v188
	v_and_b32_e32 v128, 24, v8
	v_writelane_b32 v253, s7, 41
	v_cmp_gt_u32_e64 s[6:7], 10, v123
	v_and_b32_e32 v122, 31, v188
	v_lshlrev_b32_e32 v124, 2, v188
	v_writelane_b32 v253, s6, 42
	s_waitcnt lgkmcnt(0)
	v_mul_lo_u32 v3, v188, 12
	v_add_u32_e32 v129, 0, v124
	v_writelane_b32 v253, s7, 43
	v_cmp_gt_u32_e64 s[6:7], 11, v123
	v_lshlrev_b32_e32 v126, 3, v2
	v_readlane_b32 s44, v249, 61
	v_writelane_b32 v253, s6, 44
	v_cmp_eq_u32_e64 s[4:5], 0, v188
	v_bfe_u32 v127, v188, 2, 4
	v_writelane_b32 v253, s7, 45
	v_cmp_gt_u32_e64 s[6:7], 12, v123
	v_ashrrev_i32_e32 v125, 31, v124
	v_cmp_eq_u32_e64 s[54:55], 0, v123
	v_writelane_b32 v253, s6, 46
	v_cmp_gt_u32_e64 s[56:57], 2, v123
	v_cmp_gt_u32_e64 s[58:59], 3, v123
	v_writelane_b32 v253, s7, 47
	v_cmp_gt_u32_e64 s[6:7], 13, v123
	v_cmp_gt_u32_e64 s[70:71], 4, v123
	v_cmp_gt_u32_e64 s[72:73], 5, v123
	v_writelane_b32 v253, s6, 48
	v_cmp_gt_u32_e64 s[74:75], 6, v123
	v_not_b32_e32 v145, v188
	v_writelane_b32 v253, s7, 49
	v_cmp_gt_u32_e64 s[6:7], 14, v123
	v_add_u32_e32 v189, 0x200, v188
	v_add_u32_e32 v146, v129, v3
	v_writelane_b32 v253, s6, 50
	v_cmp_gt_u32_e64 s[8:9], 59, v123
	v_cmp_gt_u32_e64 s[10:11], 60, v123
	v_writelane_b32 v253, s7, 51
	v_cmp_gt_u32_e64 s[6:7], 15, v123
	v_cmp_eq_u32_e64 s[38:39], 63, v123
	v_readlane_b32 s45, v249, 62
	v_writelane_b32 v253, s6, 52
	s_movk_i32 s46, 0x3ff
	v_readlane_b32 s47, v251, 14
	v_writelane_b32 v253, s7, 53
	v_cmp_gt_u32_e64 s[6:7], 16, v123
	v_readlane_b32 s48, v251, 15
	v_readlane_b32 s49, v251, 33
	v_writelane_b32 v253, s6, 54
	s_mov_b64 s[50:51], 0x800
	s_waitcnt vmcnt(0)
	v_mul_f32_e32 v9, v4, v5
	ds_bpermute_b32 v9, v219, v9
	v_mul_f32_e32 v10, v6, v7
	ds_bpermute_b32 v10, v219, v10
	v_writelane_b32 v253, s7, 55
	v_cmp_gt_u32_e64 s[6:7], 17, v123
	s_waitcnt lgkmcnt(1)
	v_fmac_f32_e32 v9, v4, v5
	ds_bpermute_b32 v4, v220, v9
	s_waitcnt lgkmcnt(1)
	v_fmac_f32_e32 v10, v6, v7
	ds_bpermute_b32 v5, v220, v10
	v_writelane_b32 v253, s6, 56
	v_cvt_f32_i32_e32 v6, s0
	s_waitcnt lgkmcnt(1)
	v_add_f32_e32 v4, v9, v4
	v_writelane_b32 v253, s7, 57
	v_cmp_gt_u32_e64 s[6:7], 18, v123
	s_waitcnt lgkmcnt(0)
	v_add_f32_e32 v5, v10, v5
	ds_bpermute_b32 v7, v221, v4
	v_writelane_b32 v253, s6, 58
	ds_bpermute_b32 v9, v221, v5
	v_readlane_b32 s0, v252, 9
	v_writelane_b32 v253, s7, 59
	v_cmp_gt_u32_e64 s[6:7], 19, v123
	s_waitcnt lgkmcnt(1)
	v_add_f32_e32 v4, v4, v7
	s_waitcnt lgkmcnt(0)
	v_add_f32_e32 v5, v5, v9
	v_writelane_b32 v253, s6, 60
	ds_bpermute_b32 v7, v222, v4
	ds_bpermute_b32 v9, v222, v5
	v_writelane_b32 v253, s7, 61
	v_cmp_gt_u32_e64 s[6:7], 20, v123
	v_mul_f32_e32 v6, 0xbe99999a, v6
	s_waitcnt lgkmcnt(1)
	v_add_f32_e32 v4, v4, v7
	v_writelane_b32 v253, s6, 62
	s_waitcnt lgkmcnt(0)
	v_add_f32_e32 v5, v5, v9
	ds_bpermute_b32 v7, v223, v4
	v_writelane_b32 v253, s7, 63
	v_cmp_gt_u32_e64 s[6:7], 21, v123
	ds_bpermute_b32 v9, v223, v5
	s_addc_u32 s53, s0, s3
	v_writelane_b32 v254, s6, 0
	v_mul_f32_e32 v10, 0x3fb8aa3b, v6
	s_mov_b32 s0, 0x3fb8aa3b
	v_writelane_b32 v254, s7, 1
	v_cmp_gt_u32_e64 s[6:7], 22, v123
	s_waitcnt lgkmcnt(1)
	v_add_f32_e32 v4, v4, v7
	v_fma_f32 v11, v6, s0, -v10
	v_writelane_b32 v254, s6, 2
	v_rndne_f32_e32 v12, v10
	s_waitcnt lgkmcnt(0)
	v_add_f32_e32 v5, v5, v9
	v_writelane_b32 v254, s7, 3
	v_cmp_gt_u32_e64 s[6:7], 23, v123
	ds_bpermute_b32 v7, v224, v4
	v_fmac_f32_e32 v11, 0x32a5705f, v6
	v_writelane_b32 v254, s6, 4
	v_sub_f32_e32 v10, v10, v12
	ds_bpermute_b32 v9, v224, v5
	v_writelane_b32 v254, s7, 5
	v_cmp_gt_u32_e64 s[6:7], 24, v123
	v_add_f32_e32 v10, v10, v11
	v_cvt_i32_f32_e32 v12, v12
	v_writelane_b32 v254, s6, 6
	v_exp_f32_e32 v10, v10
	s_waitcnt lgkmcnt(1)
	v_add_f32_e32 v4, v4, v7
	v_writelane_b32 v254, s7, 7
	v_cmp_gt_u32_e64 s[6:7], 25, v123
	s_waitcnt lgkmcnt(0)
; #define LAS __attribute__((address_space(3)))
; template <int DV, int NMAP>
; __device__ __forceinline__ void attn_unit(LAS unsigned char* lds, const bf16_t* U, bf16_t* MIX, const float* logf, int b, int h, int qb, float lam, float slope2, const float* gn, float outscale, const int tid) {
;     ...
;             float incl = 0.f, wsum = 0.f;
; #pragma unroll
;             for (int j4 = 0; j4 < 16; ++j4) { const f32x4 t = *(const LAS f32x4*)(tots + wid * 64 + 4 * j4);
; #pragma unroll
;                 for (int i = 0; i < 4; ++i) { wsum += t[i]; incl += (4 * j4 + i <= lane) ? t[i] : 0.f; } }
; __device__ __forceinline__ void attn_phase(const Args& a, int l, LAS unsigned char* lds, const int tid, const int rep) {
;     ...
;     const float lam_init = 0.8f - 0.6f * expf(-0.3f * (float)lop);
;     float lam;
;     {
;         const float* lv = a.in[10] + l * 256;
;         const float sa = wave_sum(lv[lane] * lv[64 + lane]), sb = wave_sum(lv[128 + lane] * lv[192 + lane]);
;         lam = expf(sa) - expf(sb) + lam_init;
;     }
;     const float* gn = a.in[11] + l * 128;
	v_add_f32_e32 v5, v5, v9
	v_mul_f32_e32 v7, 0x3fb8aa3b, v4
	v_writelane_b32 v254, s6, 8
	v_ldexp_f32 v10, v10, v12
	v_mul_f32_e32 v9, 0x3fb8aa3b, v5
	v_writelane_b32 v254, s7, 9
	v_cmp_gt_u32_e64 s[6:7], 26, v123
	v_fma_f32 v11, v4, s0, -v7
	v_rndne_f32_e32 v12, v7
	v_writelane_b32 v254, s6, 10
	v_fma_f32 v13, v5, s0, -v9
	v_rndne_f32_e32 v14, v9
	v_writelane_b32 v254, s7, 11
	v_cmp_gt_u32_e64 s[6:7], 27, v123
	v_fmac_f32_e32 v11, 0x32a5705f, v4
	v_sub_f32_e32 v7, v7, v12
	v_writelane_b32 v254, s6, 12
	v_fmac_f32_e32 v13, 0x32a5705f, v5
	v_sub_f32_e32 v9, v9, v14
	v_writelane_b32 v254, s7, 13
	v_cmp_gt_u32_e64 s[6:7], 28, v123
	v_add_f32_e32 v7, v7, v11
	v_cvt_i32_f32_e32 v12, v12
	v_writelane_b32 v254, s6, 14
	v_add_f32_e32 v9, v9, v13
	v_exp_f32_e32 v7, v7
	v_writelane_b32 v254, s7, 15
	v_cmp_gt_u32_e64 s[6:7], 29, v123
	v_cvt_i32_f32_e32 v14, v14
	v_exp_f32_e32 v9, v9
	v_writelane_b32 v254, s6, 16
	v_cmp_ngt_f32_e32 vcc, s1, v6
	s_mov_b32 s0, 0x42b17218
	v_writelane_b32 v254, s7, 17
	v_cmp_gt_u32_e64 s[6:7], 30, v123
	v_cndmask_b32_e32 v10, 0, v10, vcc
	v_cmp_nlt_f32_e32 vcc, s0, v6
	v_writelane_b32 v254, s6, 18
	v_ldexp_f32 v7, v7, v12
	v_cndmask_b32_e32 v6, v229, v10, vcc
	v_writelane_b32 v254, s7, 19
	v_cmp_gt_u32_e64 s[6:7], 31, v123
	v_cmp_ngt_f32_e32 vcc, s1, v4
	v_ldexp_f32 v9, v9, v14
	v_writelane_b32 v254, s6, 20
	v_cndmask_b32_e32 v7, 0, v7, vcc
	v_cmp_ngt_f32_e32 vcc, s1, v5
	v_writelane_b32 v254, s7, 21
	v_cmp_gt_u32_e64 s[6:7], 32, v123
	v_cndmask_b32_e32 v9, 0, v9, vcc
	v_cmp_nlt_f32_e32 vcc, s0, v4
	v_writelane_b32 v254, s6, 22
	v_fmamk_f32 v6, v6, 0xbf19999a, v0
	v_cndmask_b32_e32 v4, v229, v7, vcc
	v_writelane_b32 v254, s7, 23
	v_cmp_gt_u32_e64 s[6:7], 33, v123
	v_cmp_nlt_f32_e32 vcc, s0, v5
	v_cmp_gt_u32_e64 s[0:1], 37, v123
	v_writelane_b32 v254, s6, 24
	v_cndmask_b32_e32 v5, v229, v9, vcc
	v_sub_f32_e32 v0, v4, v5
	v_writelane_b32 v254, s7, 25
	v_cmp_gt_u32_e64 s[6:7], 34, v123
	v_add_f32_e32 v140, v6, v0
	v_lshrrev_b32_e32 v0, 2, v188
	v_writelane_b32 v254, s6, 26
	v_and_or_b32 v0, v0, 3, v130
	v_lshlrev_b32_e32 v4, 1, v188
	v_writelane_b32 v254, s7, 27
	v_cmp_gt_u32_e64 s[6:7], 35, v123
	v_and_b32_e32 v4, 32, v4
	v_lshl_add_u32 v0, v0, 6, 0
	v_writelane_b32 v254, s6, 28
	v_add3_u32 v141, v0, v4, v128
	v_lshlrev_b32_e32 v0, 4, v2
	v_writelane_b32 v254, s7, 29
	v_cmp_gt_u32_e64 s[6:7], 36, v123
	v_add_u32_e32 v142, 0, v0
	v_lshlrev_b32_e32 v4, 4, v122
	v_writelane_b32 v254, s6, 30
	v_mul_u32_u24_e32 v2, 0x420, v2
	v_add3_u32 v143, 0, v4, v2
	v_writelane_b32 v254, s7, 31
	v_writelane_b32 v254, s0, 32
	v_sub_f32_e32 v144, 1.0, v6
	v_cmp_gt_u32_e64 s[6:7], 58, v123
	v_writelane_b32 v254, s1, 33
	v_readlane_b32 s0, v252, 22
	v_readlane_b32 s1, v252, 23
	v_cmp_gt_u32_e64 s[2:3], 62, v123
	s_nop 0
	v_lshl_add_u64 v[132:133], s[0:1], 0, v[0:1]
	v_and_b32_e32 v0, 3, v188
	v_readlane_b32 s0, v251, 16
	v_lshlrev_b32_e32 v0, 4, v0
	v_readlane_b32 s1, v251, 17
	s_nop 1
	v_lshl_add_u64 v[134:135], s[0:1], 0, v[0:1]
	v_cmp_gt_u32_e64 s[0:1], 38, v123
	s_nop 1
	v_writelane_b32 v254, s0, 34
	s_nop 1
	v_writelane_b32 v254, s1, 35
	v_cmp_gt_u32_e64 s[0:1], 39, v123
	s_nop 1
	v_writelane_b32 v254, s0, 36
	s_nop 1
	v_writelane_b32 v254, s1, 37
	v_cmp_gt_u32_e64 s[0:1], 40, v123
	s_nop 1
	v_writelane_b32 v254, s0, 38
	s_nop 1
	v_writelane_b32 v254, s1, 39
	v_cmp_gt_u32_e64 s[0:1], 41, v123
	s_nop 1
	v_writelane_b32 v254, s0, 40
	s_nop 1
	v_writelane_b32 v254, s1, 41
	v_cmp_gt_u32_e64 s[0:1], 42, v123
	s_nop 1
	v_writelane_b32 v254, s0, 42
	s_nop 1
	v_writelane_b32 v254, s1, 43
	v_cmp_gt_u32_e64 s[0:1], 43, v123
	s_nop 1
	v_writelane_b32 v254, s0, 44
	s_nop 1
	v_writelane_b32 v254, s1, 45
	v_cmp_gt_u32_e64 s[0:1], 44, v123
	s_nop 1
	v_writelane_b32 v254, s0, 46
	s_nop 1
	v_writelane_b32 v254, s1, 47
	v_cmp_gt_u32_e64 s[0:1], 45, v123
	s_nop 1
	v_writelane_b32 v254, s0, 48
	s_nop 1
	v_writelane_b32 v254, s1, 49
	v_cmp_gt_u32_e64 s[0:1], 46, v123
	s_nop 1
	v_writelane_b32 v254, s0, 50
	s_nop 1
	v_writelane_b32 v254, s1, 51
	v_cmp_gt_u32_e64 s[0:1], 47, v123
	s_nop 1
	v_writelane_b32 v254, s0, 52
	s_nop 1
	v_writelane_b32 v254, s1, 53
	v_cmp_gt_u32_e64 s[0:1], 48, v123
	s_nop 1
	v_writelane_b32 v254, s0, 54
	s_nop 1
	v_writelane_b32 v254, s1, 55
	v_cmp_gt_u32_e64 s[0:1], 49, v123
	s_nop 1
	v_writelane_b32 v254, s0, 56
	s_nop 1
	v_writelane_b32 v254, s1, 57
	v_cmp_gt_u32_e64 s[0:1], 50, v123
	s_nop 1
	v_writelane_b32 v254, s0, 58
	s_nop 1
	v_writelane_b32 v254, s1, 59
	v_cmp_gt_u32_e64 s[0:1], 51, v123
	s_nop 1
	v_writelane_b32 v254, s0, 60
	s_nop 1
	v_writelane_b32 v254, s1, 61
	v_cmp_gt_u32_e64 s[0:1], 52, v123
	s_nop 1
	v_writelane_b32 v254, s0, 62
	s_nop 1
	v_writelane_b32 v254, s1, 63
	v_cmp_gt_u32_e64 s[0:1], 53, v123
	s_nop 1
	v_writelane_b32 v255, s0, 0
	s_nop 1
	v_writelane_b32 v255, s1, 1
	v_cmp_gt_u32_e64 s[0:1], 54, v123
	s_nop 1
	v_writelane_b32 v255, s0, 2
	s_nop 1
	v_writelane_b32 v255, s1, 3
	v_cmp_gt_u32_e64 s[0:1], 55, v123
	s_nop 1
	v_writelane_b32 v255, s0, 4
	s_nop 1
	v_writelane_b32 v255, s1, 5
	v_cmp_gt_u32_e64 s[0:1], 56, v123
	s_nop 1
	v_writelane_b32 v255, s0, 6
	s_nop 1
	v_writelane_b32 v255, s1, 7
	v_cmp_gt_u32_e64 s[0:1], 57, v123
	s_nop 1
	v_writelane_b32 v255, s0, 8
	s_nop 1
	v_writelane_b32 v255, s1, 9
	v_cmp_gt_u32_e64 s[0:1], 61, v123
	v_writelane_b32 v255, s21, 20
	s_branch .LBB0_178
